# SSD scan: STATES loads marked nt (streamed once) on top of the scan / A pass 2 wave-order swap
# baseline (speedup 1.0000x reference)
; DI void ssd_scan(float* STATES, const float* TOT, int gtid, int gthreads) {
;     for (int it = gtid; it < 8 * 4 * 2 * 64 * 32; it += gthreads) {
;         const int n4 = it & 31, p = (it >> 5) & 63, dir = (it >> 11) & 1, h = (it >> 12) & 3, b = it >> 14;
;         f32x4 v[16]; float e[16];
; #pragma unroll
;         for (int st = 0; st < 16; ++st) { const int c = dir ? 15 - st : st; const int hd = ((b * 16 + c) * 4 + h) * 2 + dir;
;             v[st] = *(const f32x4*)(STATES + ((size_t)hd * 64 + p) * 128 + n4 * 4); e[st] = __expf(TOT[hd]); }
.LBB0_418:
	v_and_b32_e32 v6, 0x1f80, v5
	v_lshlrev_b32_e32 v188, 2, v6
	v_and_b32_e32 v10, 0x7c, v5
	v_lshrrev_b32_e32 v8, 11, v4
	v_lshl_add_u64 v[6:7], s[12:13], 0, v[188:189]
	v_lshlrev_b32_e32 v188, 2, v10
	v_bfe_i32 v9, v4, 11, 1
	v_lshl_add_u64 v[66:67], v[6:7], 0, v[188:189]
	v_ashrrev_i32_e32 v7, 7, v4
	v_and_b32_e32 v8, 6, v8
	s_movk_i32 s2, 0xff80
	v_bfe_u32 v73, v4, 11, 1
	v_and_b32_e32 v6, 0x78, v9
	v_and_or_b32 v77, v7, s2, v8
	v_or3_b32 v10, v73, v6, v77
	v_ashrrev_i32_e32 v11, 31, v10
	v_lshlrev_b64 v[6:7], 15, v[10:11]
	v_lshl_add_u64 v[68:69], v[66:67], 0, v[6:7]
	v_lshl_add_u64 v[10:11], v[10:11], 2, s[70:71]
	global_load_dwordx4 v[6:9], v[68:69], off nt
	v_cmp_eq_u32_e32 vcc, 0, v73
	global_load_dword v10, v[10:11], off
	v_lshlrev_b32_e32 v40, 3, v73
	v_add_u32_e32 v4, s56, v4
	s_mov_b32 s2, 0x1ffff
	v_add_u32_e32 v5, s75, v5
	s_waitcnt vmcnt(0)
	v_mul_f32_e32 v10, 0x3fb8aa3b, v10
	v_exp_f32_e32 v81, v10
	v_cndmask_b32_e64 v10, v235, 8, vcc
	v_or3_b32 v14, v73, v10, v77
	v_ashrrev_i32_e32 v15, 31, v14
	v_lshlrev_b64 v[10:11], 15, v[14:15]
	v_lshl_add_u64 v[70:71], v[66:67], 0, v[10:11]
	v_lshl_add_u64 v[14:15], v[14:15], 2, s[70:71]
	global_load_dwordx4 v[10:13], v[70:71], off nt
	s_nop 0
	global_load_dword v14, v[14:15], off
	s_waitcnt vmcnt(0)
	v_mul_f32_e32 v14, 0x3fb8aa3b, v14
	v_exp_f32_e32 v72, v14
	v_cndmask_b32_e64 v14, v236, 16, vcc
	v_or3_b32 v18, v73, v14, v77
	v_ashrrev_i32_e32 v19, 31, v18
	v_lshlrev_b64 v[14:15], 15, v[18:19]
	v_lshl_add_u64 v[74:75], v[66:67], 0, v[14:15]
	v_lshl_add_u64 v[18:19], v[18:19], 2, s[70:71]
	global_load_dwordx4 v[14:17], v[74:75], off nt
	s_nop 0
	global_load_dword v18, v[18:19], off
	s_waitcnt vmcnt(0)
	v_mul_f32_e32 v18, 0x3fb8aa3b, v18
	v_exp_f32_e32 v76, v18
	v_cndmask_b32_e64 v18, v237, 24, vcc
	v_or3_b32 v22, v73, v18, v77
	v_ashrrev_i32_e32 v23, 31, v22
	v_lshlrev_b64 v[18:19], 15, v[22:23]
	v_lshl_add_u64 v[78:79], v[66:67], 0, v[18:19]
	v_lshl_add_u64 v[22:23], v[22:23], 2, s[70:71]
	global_load_dwordx4 v[18:21], v[78:79], off nt
	s_nop 0
	global_load_dword v22, v[22:23], off
	s_waitcnt vmcnt(0)
	v_mul_f32_e32 v22, 0x3fb8aa3b, v22
	v_exp_f32_e32 v80, v22
	v_cndmask_b32_e64 v22, v238, 32, vcc
	v_or3_b32 v26, v73, v22, v77
	v_ashrrev_i32_e32 v27, 31, v26
	v_lshlrev_b64 v[22:23], 15, v[26:27]
	v_lshl_add_u64 v[82:83], v[66:67], 0, v[22:23]
	v_lshl_add_u64 v[26:27], v[26:27], 2, s[70:71]
	global_load_dwordx4 v[22:25], v[82:83], off nt
	s_nop 0
	global_load_dword v26, v[26:27], off
	s_waitcnt vmcnt(0)
	v_mul_f32_e32 v26, 0x3fb8aa3b, v26
	v_exp_f32_e32 v84, v26
	v_cndmask_b32_e64 v26, v239, 40, vcc
	v_or3_b32 v30, v73, v26, v77
	v_ashrrev_i32_e32 v31, 31, v30
	v_lshlrev_b64 v[26:27], 15, v[30:31]
	v_lshl_add_u64 v[86:87], v[66:67], 0, v[26:27]
	v_lshl_add_u64 v[30:31], v[30:31], 2, s[70:71]
	global_load_dwordx4 v[26:29], v[86:87], off nt
	s_nop 0
	global_load_dword v30, v[30:31], off
	s_waitcnt vmcnt(0)
	v_mul_f32_e32 v30, 0x3fb8aa3b, v30
	v_exp_f32_e32 v88, v30
	v_cndmask_b32_e64 v30, v240, 48, vcc
	v_or3_b32 v34, v73, v30, v77
	v_ashrrev_i32_e32 v35, 31, v34
	v_lshlrev_b64 v[30:31], 15, v[34:35]
	v_lshl_add_u64 v[90:91], v[66:67], 0, v[30:31]
	v_lshl_add_u64 v[34:35], v[34:35], 2, s[70:71]
	global_load_dwordx4 v[30:33], v[90:91], off nt
	s_nop 0
	global_load_dword v34, v[34:35], off
	s_waitcnt vmcnt(0)
	v_mul_f32_e32 v34, 0x3fb8aa3b, v34
	v_exp_f32_e32 v92, v34
	v_or3_b32 v34, v40, v77, v73
	v_add_u32_e32 v38, 56, v34
	v_ashrrev_i32_e32 v39, 31, v38
	v_lshlrev_b64 v[34:35], 15, v[38:39]
	v_lshl_add_u64 v[94:95], v[66:67], 0, v[34:35]
	v_lshl_add_u64 v[38:39], v[38:39], 2, s[70:71]
	global_load_dwordx4 v[34:37], v[94:95], off nt
	s_nop 0
	global_load_dword v38, v[38:39], off
	s_waitcnt vmcnt(0)
	v_mul_f32_e32 v38, 0x3fb8aa3b, v38
	v_exp_f32_e32 v96, v38
	v_or_b32_e32 v38, 64, v73
	v_sub_u32_e32 v38, v38, v40
	v_or_b32_e32 v42, v38, v77
	v_ashrrev_i32_e32 v43, 31, v42
	v_lshlrev_b64 v[38:39], 15, v[42:43]
	v_lshl_add_u64 v[98:99], v[66:67], 0, v[38:39]
	v_lshl_add_u64 v[42:43], v[42:43], 2, s[70:71]
	global_load_dwordx4 v[38:41], v[98:99], off nt
	s_nop 0
	global_load_dword v42, v[42:43], off
	s_waitcnt vmcnt(0)
	v_mul_f32_e32 v42, 0x3fb8aa3b, v42
	v_exp_f32_e32 v100, v42
	v_cndmask_b32_e32 v42, 48, v240, vcc
	v_or3_b32 v46, v73, v42, v77
	v_ashrrev_i32_e32 v47, 31, v46
	v_lshlrev_b64 v[42:43], 15, v[46:47]
	v_lshl_add_u64 v[102:103], v[66:67], 0, v[42:43]
	v_lshl_add_u64 v[46:47], v[46:47], 2, s[70:71]
	global_load_dwordx4 v[42:45], v[102:103], off nt
	s_nop 0
	global_load_dword v46, v[46:47], off
	s_waitcnt vmcnt(0)
	v_mul_f32_e32 v46, 0x3fb8aa3b, v46
	v_exp_f32_e32 v104, v46
	v_cndmask_b32_e32 v46, 40, v239, vcc
	v_or3_b32 v50, v73, v46, v77
	v_ashrrev_i32_e32 v51, 31, v50
	v_lshlrev_b64 v[46:47], 15, v[50:51]
	v_lshl_add_u64 v[106:107], v[66:67], 0, v[46:47]
	v_lshl_add_u64 v[50:51], v[50:51], 2, s[70:71]
	global_load_dwordx4 v[46:49], v[106:107], off nt
	s_nop 0
	global_load_dword v50, v[50:51], off
	s_waitcnt vmcnt(0)
; DI void ssd_scan(float* STATES, const float* TOT, int gtid, int gthreads) {
;     ...
;         for (int st = 0; st < 16; ++st) { const int c = dir ? 15 - st : st; const int hd = ((b * 16 + c) * 4 + h) * 2 + dir;
;             v[st] = *(const f32x4*)(STATES + ((size_t)hd * 64 + p) * 128 + n4 * 4); e[st] = __expf(TOT[hd]); }
;         f32x4 carry = (f32x4){0.f, 0.f, 0.f, 0.f};
; #pragma unroll
;         for (int st = 0; st < 16; ++st) { const int c = dir ? 15 - st : st; const int hd = ((b * 16 + c) * 4 + h) * 2 + dir;
;             *(f32x4*)(STATES + ((size_t)hd * 64 + p) * 128 + n4 * 4) = carry; carry = carry * e[st] + v[st]; }
	v_mul_f32_e32 v50, 0x3fb8aa3b, v50
	v_exp_f32_e32 v108, v50
	v_cndmask_b32_e32 v50, 32, v238, vcc
	v_or3_b32 v54, v73, v50, v77
	v_ashrrev_i32_e32 v55, 31, v54
	v_lshlrev_b64 v[50:51], 15, v[54:55]
	v_lshl_add_u64 v[110:111], v[66:67], 0, v[50:51]
	v_lshl_add_u64 v[54:55], v[54:55], 2, s[70:71]
	global_load_dwordx4 v[50:53], v[110:111], off nt
	s_nop 0
	global_load_dword v54, v[54:55], off
	s_waitcnt vmcnt(0)
	v_mul_f32_e32 v54, 0x3fb8aa3b, v54
	v_exp_f32_e32 v112, v54
	v_cndmask_b32_e32 v54, 24, v237, vcc
	v_or3_b32 v58, v73, v54, v77
	v_ashrrev_i32_e32 v59, 31, v58
	v_lshlrev_b64 v[54:55], 15, v[58:59]
	v_lshl_add_u64 v[114:115], v[66:67], 0, v[54:55]
	v_lshl_add_u64 v[58:59], v[58:59], 2, s[70:71]
	global_load_dwordx4 v[54:57], v[114:115], off nt
	s_nop 0
	global_load_dword v58, v[58:59], off
	s_waitcnt vmcnt(0)
	v_mul_f32_e32 v58, 0x3fb8aa3b, v58
	v_exp_f32_e32 v116, v58
	v_cndmask_b32_e32 v58, 16, v236, vcc
	v_or3_b32 v62, v73, v58, v77
	v_ashrrev_i32_e32 v63, 31, v62
	v_lshlrev_b64 v[58:59], 15, v[62:63]
	v_lshl_add_u64 v[118:119], v[66:67], 0, v[58:59]
	v_lshl_add_u64 v[62:63], v[62:63], 2, s[70:71]
	global_load_dwordx4 v[58:61], v[118:119], off nt
	s_nop 0
	global_load_dword v62, v[62:63], off
	s_waitcnt vmcnt(0)
	v_mul_f32_e32 v62, 0x3fb8aa3b, v62
	v_exp_f32_e32 v120, v62
	v_cndmask_b32_e32 v62, 8, v235, vcc
	v_or3_b32 v122, v73, v62, v77
	v_ashrrev_i32_e32 v123, 31, v122
	v_lshlrev_b64 v[62:63], 15, v[122:123]
	v_lshl_add_u64 v[124:125], v[66:67], 0, v[62:63]
	v_lshl_add_u64 v[122:123], v[122:123], 2, s[70:71]
	global_load_dwordx4 v[62:65], v[124:125], off nt
	global_load_dword v85, v[122:123], off
	s_waitcnt vmcnt(0)
	v_mul_f32_e32 v85, 0x3fb8aa3b, v85
	global_store_dwordx4 v[68:69], v[0:3], off
	v_mul_f32_e32 v68, 0, v81
	v_pk_add_f32 v[8:9], v[8:9], v[68:69] op_sel_hi:[1,0]
	v_pk_add_f32 v[6:7], v[6:7], v[68:69] op_sel_hi:[1,0]
	global_store_dwordx4 v[70:71], v[6:9], off
	v_exp_f32_e32 v122, v85
	v_cndmask_b32_e32 v85, 0, v241, vcc
	v_pk_fma_f32 v[8:9], v[8:9], v[72:73], v[12:13] op_sel_hi:[1,0,1]
	v_pk_fma_f32 v[6:7], v[6:7], v[72:73], v[10:11] op_sel_hi:[1,0,1]
	global_store_dwordx4 v[74:75], v[6:9], off
	v_or3_b32 v126, v73, v85, v77
	v_ashrrev_i32_e32 v127, 31, v126
	v_pk_fma_f32 v[8:9], v[8:9], v[76:77], v[16:17] op_sel_hi:[1,0,1]
	v_pk_fma_f32 v[6:7], v[6:7], v[76:77], v[14:15] op_sel_hi:[1,0,1]
	global_store_dwordx4 v[78:79], v[6:9], off
	v_lshlrev_b64 v[10:11], 15, v[126:127]
	v_cmp_lt_i32_e32 vcc, s2, v4
	v_pk_fma_f32 v[8:9], v[8:9], v[80:81], v[20:21] op_sel_hi:[1,0,1]
	v_pk_fma_f32 v[6:7], v[6:7], v[80:81], v[18:19] op_sel_hi:[1,0,1]
	global_store_dwordx4 v[82:83], v[6:9], off
	v_lshl_add_u64 v[10:11], v[66:67], 0, v[10:11]
	s_or_b64 s[20:21], vcc, s[20:21]
	v_pk_fma_f32 v[8:9], v[8:9], v[84:85], v[24:25] op_sel_hi:[1,0,1]
	v_pk_fma_f32 v[6:7], v[6:7], v[84:85], v[22:23] op_sel_hi:[1,0,1]
	global_store_dwordx4 v[86:87], v[6:9], off
	s_nop 1
	v_pk_fma_f32 v[8:9], v[8:9], v[88:89], v[28:29] op_sel_hi:[1,0,1]
	v_pk_fma_f32 v[6:7], v[6:7], v[88:89], v[26:27] op_sel_hi:[1,0,1]
	global_store_dwordx4 v[90:91], v[6:9], off
	s_nop 1
	v_pk_fma_f32 v[8:9], v[8:9], v[92:93], v[32:33] op_sel_hi:[1,0,1]
	v_pk_fma_f32 v[6:7], v[6:7], v[92:93], v[30:31] op_sel_hi:[1,0,1]
	global_store_dwordx4 v[94:95], v[6:9], off
	s_nop 1
	v_pk_fma_f32 v[8:9], v[8:9], v[96:97], v[36:37] op_sel_hi:[1,0,1]
	v_pk_fma_f32 v[6:7], v[6:7], v[96:97], v[34:35] op_sel_hi:[1,0,1]
	global_store_dwordx4 v[98:99], v[6:9], off
	s_nop 1
	v_pk_fma_f32 v[8:9], v[8:9], v[100:101], v[40:41] op_sel_hi:[1,0,1]
	v_pk_fma_f32 v[6:7], v[6:7], v[100:101], v[38:39] op_sel_hi:[1,0,1]
	global_store_dwordx4 v[102:103], v[6:9], off
	s_nop 1
	v_pk_fma_f32 v[8:9], v[8:9], v[104:105], v[44:45] op_sel_hi:[1,0,1]
	v_pk_fma_f32 v[6:7], v[6:7], v[104:105], v[42:43] op_sel_hi:[1,0,1]
	global_store_dwordx4 v[106:107], v[6:9], off
	s_nop 1
	v_pk_fma_f32 v[8:9], v[8:9], v[108:109], v[48:49] op_sel_hi:[1,0,1]
	v_pk_fma_f32 v[6:7], v[6:7], v[108:109], v[46:47] op_sel_hi:[1,0,1]
	global_store_dwordx4 v[110:111], v[6:9], off
	s_nop 1
	v_pk_fma_f32 v[8:9], v[8:9], v[112:113], v[52:53] op_sel_hi:[1,0,1]
	v_pk_fma_f32 v[6:7], v[6:7], v[112:113], v[50:51] op_sel_hi:[1,0,1]
	global_store_dwordx4 v[114:115], v[6:9], off
	s_nop 1
	v_pk_fma_f32 v[8:9], v[8:9], v[116:117], v[56:57] op_sel_hi:[1,0,1]
	v_pk_fma_f32 v[6:7], v[6:7], v[116:117], v[54:55] op_sel_hi:[1,0,1]
	global_store_dwordx4 v[118:119], v[6:9], off
	s_nop 1
	v_pk_fma_f32 v[8:9], v[8:9], v[120:121], v[60:61] op_sel_hi:[1,0,1]
	v_pk_fma_f32 v[6:7], v[6:7], v[120:121], v[58:59] op_sel_hi:[1,0,1]
	global_store_dwordx4 v[124:125], v[6:9], off
	s_nop 1
	v_pk_fma_f32 v[8:9], v[8:9], v[122:123], v[64:65] op_sel_hi:[1,0,1]
	v_pk_fma_f32 v[6:7], v[6:7], v[122:123], v[62:63] op_sel_hi:[1,0,1]
	global_store_dwordx4 v[10:11], v[6:9], off
	s_andn2_b64 exec, exec, s[20:21]
	s_cbranch_execnz .LBB0_418
